# stack4 plus: the last-arriving XCD leader releases the local workgroups of every XCD itself (16 XGEN atomics) instead of each leader polling then releasing its own
# baseline (speedup 1.0000x reference)
.LBB0_109:
	s_or_b64 exec, exec, s[12:13]
	s_and_saveexec_b64 s[6:7], s[14:15]
	s_cbranch_execz .LBB0_111
	v_mov_b32_e32 v1, 1
	global_atomic_add v[2:3], v1, off
	v_mov_b32_e32 v5, 0
	global_atomic_add v5, v1, s[100:101] offset:-4096
	global_atomic_add v5, v1, s[100:101] offset:-3840
	global_atomic_add v5, v1, s[100:101] offset:-3584
	global_atomic_add v5, v1, s[100:101] offset:-3328
	global_atomic_add v5, v1, s[100:101] offset:-3072
	global_atomic_add v5, v1, s[100:101] offset:-2816
	global_atomic_add v5, v1, s[100:101] offset:-2560
	global_atomic_add v5, v1, s[100:101] offset:-2304
	global_atomic_add v5, v1, s[100:101] offset:-2048
	global_atomic_add v5, v1, s[100:101] offset:-1792
	global_atomic_add v5, v1, s[100:101] offset:-1536
	global_atomic_add v5, v1, s[100:101] offset:-1280
	global_atomic_add v5, v1, s[100:101] offset:-1024
	global_atomic_add v5, v1, s[100:101] offset:-768
	global_atomic_add v5, v1, s[100:101] offset:-512
	global_atomic_add v5, v1, s[100:101] offset:-256
.LBB0_111:
	s_or_b64 exec, exec, s[6:7]
	s_mov_b64 s[6:7], exec
	v_mbcnt_lo_u32_b32 v1, s6, 0
	v_mbcnt_hi_u32_b32 v1, s7, v1
	v_cmp_eq_u32_e32 vcc, 0, v1
	s_and_saveexec_b64 s[10:11], vcc
	s_cbranch_execz .LBB0_113
	s_bcnt1_i32_b64 s6, s[6:7]
	v_mov_b32_e32 v1, 0
	v_mov_b32_e32 v2, s6
.LBB0_113:
	s_or_b64 exec, exec, s[10:11]
	s_waitcnt vmcnt(0)

.LBB0_205:
	s_or_b64 exec, exec, s[6:7]
	s_mov_b64 s[6:7], exec
	v_mbcnt_lo_u32_b32 v1, s6, 0
	v_mbcnt_hi_u32_b32 v1, s7, v1
	v_cmp_eq_u32_e32 vcc, 0, v1
	s_and_saveexec_b64 s[10:11], vcc
	s_cbranch_execz .LBB0_207
	s_bcnt1_i32_b64 s6, s[6:7]
	v_mov_b32_e32 v1, 0
	v_mov_b32_e32 v2, s6
.LBB0_207:
	s_or_b64 exec, exec, s[10:11]
	s_waitcnt vmcnt(0)

.LBB0_302:
	s_or_b64 exec, exec, s[6:7]
	s_mov_b64 s[6:7], exec
	v_mbcnt_lo_u32_b32 v1, s6, 0
	v_mbcnt_hi_u32_b32 v1, s7, v1
	v_cmp_eq_u32_e32 vcc, 0, v1
	s_and_saveexec_b64 s[10:11], vcc
	s_cbranch_execz .LBB0_304
	s_bcnt1_i32_b64 s6, s[6:7]
	v_mov_b32_e32 v1, 0
	v_mov_b32_e32 v2, s6
.LBB0_304:
	s_or_b64 exec, exec, s[10:11]
	s_waitcnt vmcnt(0)

.LBB0_374:
	s_or_b64 exec, exec, s[6:7]
	s_mov_b64 s[6:7], exec
	v_mbcnt_lo_u32_b32 v1, s6, 0
	v_mbcnt_hi_u32_b32 v1, s7, v1
	v_cmp_eq_u32_e32 vcc, 0, v1
	s_and_saveexec_b64 s[10:11], vcc
	s_cbranch_execz .LBB0_376
	s_bcnt1_i32_b64 s6, s[6:7]
	v_mov_b32_e32 v1, 0
	v_mov_b32_e32 v2, s6
.LBB0_376:
	s_or_b64 exec, exec, s[10:11]
	s_waitcnt vmcnt(0)

.LBB0_473:
	s_or_b64 exec, exec, s[6:7]
	s_mov_b64 s[6:7], exec
	v_mbcnt_lo_u32_b32 v1, s6, 0
	v_mbcnt_hi_u32_b32 v1, s7, v1
	v_cmp_eq_u32_e32 vcc, 0, v1
	s_and_saveexec_b64 s[10:11], vcc
	s_cbranch_execz .LBB0_475
	s_bcnt1_i32_b64 s6, s[6:7]
	v_mov_b32_e32 v1, 0
	v_mov_b32_e32 v2, s6
.LBB0_475:
	s_or_b64 exec, exec, s[10:11]
	s_waitcnt vmcnt(0)

.LBB0_550:
	s_or_b64 exec, exec, s[6:7]
	s_mov_b64 s[6:7], exec
	v_mbcnt_lo_u32_b32 v1, s6, 0
	v_mbcnt_hi_u32_b32 v1, s7, v1
	v_cmp_eq_u32_e32 vcc, 0, v1
	s_and_saveexec_b64 s[10:11], vcc
	s_cbranch_execz .LBB0_552
	s_bcnt1_i32_b64 s6, s[6:7]
	v_mov_b32_e32 v1, 0
	v_mov_b32_e32 v2, s6
.LBB0_552:
	s_or_b64 exec, exec, s[10:11]
	s_waitcnt vmcnt(0)

.LBB0_631:
	s_or_b64 exec, exec, s[6:7]
	s_mov_b64 s[6:7], exec
	v_mbcnt_lo_u32_b32 v1, s6, 0
	v_mbcnt_hi_u32_b32 v1, s7, v1
	v_cmp_eq_u32_e32 vcc, 0, v1
	s_and_saveexec_b64 s[10:11], vcc
	s_cbranch_execz .LBB0_633
	s_bcnt1_i32_b64 s6, s[6:7]
	v_mov_b32_e32 v1, 0
	v_mov_b32_e32 v2, s6
.LBB0_633:
	s_or_b64 exec, exec, s[10:11]
	s_waitcnt vmcnt(0)

.LBB0_711:
	s_or_b64 exec, exec, s[6:7]
	s_mov_b64 s[6:7], exec
	v_mbcnt_lo_u32_b32 v1, s6, 0
	v_mbcnt_hi_u32_b32 v1, s7, v1
	v_cmp_eq_u32_e32 vcc, 0, v1
	s_and_saveexec_b64 s[10:11], vcc
	s_cbranch_execz .LBB0_713
	s_bcnt1_i32_b64 s6, s[6:7]
	v_mov_b32_e32 v1, 0
	v_mov_b32_e32 v2, s6
.LBB0_713:
	s_or_b64 exec, exec, s[10:11]
	s_waitcnt vmcnt(0)

.LBB0_805:
	s_or_b64 exec, exec, s[6:7]
	s_mov_b64 s[6:7], exec
	v_mbcnt_lo_u32_b32 v1, s6, 0
	v_mbcnt_hi_u32_b32 v1, s7, v1
	v_cmp_eq_u32_e32 vcc, 0, v1
	s_and_saveexec_b64 s[10:11], vcc
	s_cbranch_execz .LBB0_807
	s_bcnt1_i32_b64 s6, s[6:7]
	v_mov_b32_e32 v1, 0
	v_mov_b32_e32 v2, s6
.LBB0_807:
	s_or_b64 exec, exec, s[10:11]
	s_waitcnt vmcnt(0)

.LBB0_902:
	s_or_b64 exec, exec, s[6:7]
	s_mov_b64 s[6:7], exec
	v_mbcnt_lo_u32_b32 v1, s6, 0
	v_mbcnt_hi_u32_b32 v1, s7, v1
	v_cmp_eq_u32_e32 vcc, 0, v1
	s_and_saveexec_b64 s[10:11], vcc
	s_cbranch_execz .LBB0_904
	s_bcnt1_i32_b64 s6, s[6:7]
	v_mov_b32_e32 v1, 0
	v_mov_b32_e32 v2, s6
.LBB0_904:
	s_or_b64 exec, exec, s[10:11]
	s_waitcnt vmcnt(0)

.LBB0_982:
	s_or_b64 exec, exec, s[6:7]
	s_mov_b64 s[6:7], exec
	v_mbcnt_lo_u32_b32 v1, s6, 0
	v_mbcnt_hi_u32_b32 v1, s7, v1
	v_cmp_eq_u32_e32 vcc, 0, v1
	s_and_saveexec_b64 s[10:11], vcc
	s_cbranch_execz .LBB0_984
	s_bcnt1_i32_b64 s6, s[6:7]
	v_mov_b32_e32 v1, 0
	v_mov_b32_e32 v2, s6
.LBB0_984:
	s_or_b64 exec, exec, s[10:11]
	s_waitcnt vmcnt(0)

.LBB0_1076:
	s_or_b64 exec, exec, s[6:7]
	s_mov_b64 s[6:7], exec
	v_mbcnt_lo_u32_b32 v1, s6, 0
	v_mbcnt_hi_u32_b32 v1, s7, v1
	v_cmp_eq_u32_e32 vcc, 0, v1
	s_and_saveexec_b64 s[10:11], vcc
	s_cbranch_execz .LBB0_1078
	s_bcnt1_i32_b64 s6, s[6:7]
	v_mov_b32_e32 v1, 0
	v_mov_b32_e32 v2, s6
.LBB0_1078:
	s_or_b64 exec, exec, s[10:11]
	s_waitcnt vmcnt(0)

.LBB0_1173:
	s_or_b64 exec, exec, s[6:7]
	s_mov_b64 s[6:7], exec
	v_mbcnt_lo_u32_b32 v1, s6, 0
	v_mbcnt_hi_u32_b32 v1, s7, v1
	v_cmp_eq_u32_e32 vcc, 0, v1
	s_and_saveexec_b64 s[10:11], vcc
	s_cbranch_execz .LBB0_1175
	s_bcnt1_i32_b64 s6, s[6:7]
	v_mov_b32_e32 v1, 0
	v_mov_b32_e32 v2, s6
.LBB0_1175:
	s_or_b64 exec, exec, s[10:11]
	s_waitcnt vmcnt(0)

.LBB0_1245:
	s_or_b64 exec, exec, s[6:7]
	s_mov_b64 s[6:7], exec
	v_mbcnt_lo_u32_b32 v1, s6, 0
	v_mbcnt_hi_u32_b32 v1, s7, v1
	v_cmp_eq_u32_e32 vcc, 0, v1
	s_and_saveexec_b64 s[10:11], vcc
	s_cbranch_execz .LBB0_1247
	s_bcnt1_i32_b64 s6, s[6:7]
	v_mov_b32_e32 v1, 0
	v_mov_b32_e32 v2, s6
.LBB0_1247:
	s_or_b64 exec, exec, s[10:11]
	s_waitcnt vmcnt(0)

.LBB0_1322:
	s_or_b64 exec, exec, s[6:7]
	s_mov_b64 s[6:7], exec
	v_mbcnt_lo_u32_b32 v1, s6, 0
	v_mbcnt_hi_u32_b32 v1, s7, v1
	v_cmp_eq_u32_e32 vcc, 0, v1
	s_and_saveexec_b64 s[10:11], vcc
	s_cbranch_execz .LBB0_1324
	s_bcnt1_i32_b64 s6, s[6:7]
	v_mov_b32_e32 v1, 0
	v_mov_b32_e32 v2, s6
.LBB0_1324:
	s_or_b64 exec, exec, s[10:11]
	s_waitcnt vmcnt(0)

.LBB0_1408:
	s_or_b64 exec, exec, s[6:7]
	s_mov_b64 s[6:7], exec
	v_mbcnt_lo_u32_b32 v1, s6, 0
	v_mbcnt_hi_u32_b32 v1, s7, v1
	v_cmp_eq_u32_e32 vcc, 0, v1
	s_and_saveexec_b64 s[10:11], vcc
	s_cbranch_execz .LBB0_1410
	s_bcnt1_i32_b64 s6, s[6:7]
	v_mov_b32_e32 v1, 0
	v_mov_b32_e32 v2, s6
.LBB0_1410:
	s_or_b64 exec, exec, s[10:11]
	s_waitcnt vmcnt(0)

.LBB0_1489:
	s_or_b64 exec, exec, s[6:7]
	s_mov_b64 s[6:7], exec
	v_mbcnt_lo_u32_b32 v1, s6, 0
	v_mbcnt_hi_u32_b32 v1, s7, v1
	v_cmp_eq_u32_e32 vcc, 0, v1
	s_and_saveexec_b64 s[10:11], vcc
	s_cbranch_execz .LBB0_1491
	s_bcnt1_i32_b64 s6, s[6:7]
	v_mov_b32_e32 v1, 0
	v_mov_b32_e32 v2, s6
.LBB0_1491:
	s_or_b64 exec, exec, s[10:11]
	s_waitcnt vmcnt(0)

.LBB0_1569:
	s_or_b64 exec, exec, s[6:7]
	s_mov_b64 s[6:7], exec
	v_mbcnt_lo_u32_b32 v1, s6, 0
	v_mbcnt_hi_u32_b32 v1, s7, v1
	v_cmp_eq_u32_e32 vcc, 0, v1
	s_and_saveexec_b64 s[10:11], vcc
	s_cbranch_execz .LBB0_1571
	s_bcnt1_i32_b64 s6, s[6:7]
	v_mov_b32_e32 v1, 0
	v_mov_b32_e32 v2, s6
.LBB0_1571:
	s_or_b64 exec, exec, s[10:11]
	s_waitcnt vmcnt(0)

.LBB0_1663:
	s_or_b64 exec, exec, s[6:7]
	s_mov_b64 s[6:7], exec
	v_mbcnt_lo_u32_b32 v1, s6, 0
	v_mbcnt_hi_u32_b32 v1, s7, v1
	v_cmp_eq_u32_e32 vcc, 0, v1
	s_and_saveexec_b64 s[10:11], vcc
	s_cbranch_execz .LBB0_1665
	s_bcnt1_i32_b64 s6, s[6:7]
	v_mov_b32_e32 v1, 0
	v_mov_b32_e32 v2, s6
.LBB0_1665:
	s_or_b64 exec, exec, s[10:11]
	s_waitcnt vmcnt(0)

.LBB0_1760:
	s_or_b64 exec, exec, s[6:7]
	s_mov_b64 s[6:7], exec
	v_mbcnt_lo_u32_b32 v1, s6, 0
	v_mbcnt_hi_u32_b32 v1, s7, v1
	v_cmp_eq_u32_e32 vcc, 0, v1
	s_and_saveexec_b64 s[10:11], vcc
	s_cbranch_execz .LBB0_1762
	s_bcnt1_i32_b64 s6, s[6:7]
	v_mov_b32_e32 v1, 0
	v_mov_b32_e32 v2, s6
.LBB0_1762:
	s_or_b64 exec, exec, s[10:11]
	s_waitcnt vmcnt(0)

.LBB0_1840:
	s_or_b64 exec, exec, s[6:7]
	s_mov_b64 s[6:7], exec
	v_mbcnt_lo_u32_b32 v1, s6, 0
	v_mbcnt_hi_u32_b32 v1, s7, v1
	v_cmp_eq_u32_e32 vcc, 0, v1
	s_and_saveexec_b64 s[10:11], vcc
	s_cbranch_execz .LBB0_1842
	s_bcnt1_i32_b64 s6, s[6:7]
	v_mov_b32_e32 v1, 0
	v_mov_b32_e32 v2, s6
.LBB0_1842:
	s_or_b64 exec, exec, s[10:11]
	s_waitcnt vmcnt(0)

.LBB0_1934:
	s_or_b64 exec, exec, s[6:7]
	s_mov_b64 s[6:7], exec
	v_mbcnt_lo_u32_b32 v1, s6, 0
	v_mbcnt_hi_u32_b32 v1, s7, v1
	v_cmp_eq_u32_e32 vcc, 0, v1
	s_and_saveexec_b64 s[10:11], vcc
	s_cbranch_execz .LBB0_1936
	s_bcnt1_i32_b64 s6, s[6:7]
	v_mov_b32_e32 v1, 0
	v_mov_b32_e32 v2, s6
.LBB0_1936:
	s_or_b64 exec, exec, s[10:11]
	s_waitcnt vmcnt(0)

.LBB0_2031:
	s_or_b64 exec, exec, s[6:7]
	s_mov_b64 s[6:7], exec
	v_mbcnt_lo_u32_b32 v1, s6, 0
	v_mbcnt_hi_u32_b32 v1, s7, v1
	v_cmp_eq_u32_e32 vcc, 0, v1
	s_and_saveexec_b64 s[10:11], vcc
	s_cbranch_execz .LBB0_2033
	s_bcnt1_i32_b64 s6, s[6:7]
	v_mov_b32_e32 v1, 0
	v_mov_b32_e32 v2, s6
.LBB0_2033:
	s_or_b64 exec, exec, s[10:11]
	s_waitcnt vmcnt(0)

.LBB0_2103:
	s_or_b64 exec, exec, s[6:7]
	s_mov_b64 s[6:7], exec
	v_mbcnt_lo_u32_b32 v1, s6, 0
	v_mbcnt_hi_u32_b32 v1, s7, v1
	v_cmp_eq_u32_e32 vcc, 0, v1
	s_and_saveexec_b64 s[10:11], vcc
	s_cbranch_execz .LBB0_2105
	s_bcnt1_i32_b64 s6, s[6:7]
	v_mov_b32_e32 v1, 0
	v_mov_b32_e32 v2, s6
.LBB0_2105:
	s_or_b64 exec, exec, s[10:11]
	s_waitcnt vmcnt(0)

.LBB0_2281:
	s_or_b64 exec, exec, s[10:11]
	s_and_saveexec_b64 s[4:5], s[12:13]
	s_cbranch_execz .LBB0_2283
	v_mov_b32_e32 v1, 1
	global_atomic_add v[2:3], v1, off
	v_mov_b32_e32 v5, 0
	global_atomic_add v5, v1, s[100:101] offset:-4096
	global_atomic_add v5, v1, s[100:101] offset:-3840
	global_atomic_add v5, v1, s[100:101] offset:-3584
	global_atomic_add v5, v1, s[100:101] offset:-3328
	global_atomic_add v5, v1, s[100:101] offset:-3072
	global_atomic_add v5, v1, s[100:101] offset:-2816
	global_atomic_add v5, v1, s[100:101] offset:-2560
	global_atomic_add v5, v1, s[100:101] offset:-2304
	global_atomic_add v5, v1, s[100:101] offset:-2048
	global_atomic_add v5, v1, s[100:101] offset:-1792
	global_atomic_add v5, v1, s[100:101] offset:-1536
	global_atomic_add v5, v1, s[100:101] offset:-1280
	global_atomic_add v5, v1, s[100:101] offset:-1024
	global_atomic_add v5, v1, s[100:101] offset:-768
	global_atomic_add v5, v1, s[100:101] offset:-512
	global_atomic_add v5, v1, s[100:101] offset:-256
.LBB0_2283:
	s_or_b64 exec, exec, s[4:5]
	s_mov_b64 s[4:5], exec
	v_mbcnt_lo_u32_b32 v1, s4, 0
	v_mbcnt_hi_u32_b32 v1, s5, v1
	v_cmp_eq_u32_e32 vcc, 0, v1
	s_and_saveexec_b64 s[8:9], vcc
	s_cbranch_execz .LBB0_2285
	s_bcnt1_i32_b64 s4, s[4:5]
	v_mov_b32_e32 v1, 0
	v_mov_b32_e32 v2, s4
.LBB0_2285:
	s_or_b64 exec, exec, s[8:9]
	s_waitcnt vmcnt(0)

.LBB0_2364:
	s_or_b64 exec, exec, s[4:5]
	s_mov_b64 s[4:5], exec
	v_mbcnt_lo_u32_b32 v1, s4, 0
	v_mbcnt_hi_u32_b32 v1, s5, v1
	v_cmp_eq_u32_e32 vcc, 0, v1
	s_and_saveexec_b64 s[8:9], vcc
	s_cbranch_execz .LBB0_2366
	s_bcnt1_i32_b64 s4, s[4:5]
	v_mov_b32_e32 v1, 0
	v_mov_b32_e32 v2, s4
.LBB0_2366:
	s_or_b64 exec, exec, s[8:9]
	s_waitcnt vmcnt(0)

.LBB0_2444:
	s_or_b64 exec, exec, s[4:5]
	s_mov_b64 s[4:5], exec
	v_mbcnt_lo_u32_b32 v1, s4, 0
	v_mbcnt_hi_u32_b32 v1, s5, v1
	v_cmp_eq_u32_e32 vcc, 0, v1
	s_and_saveexec_b64 s[8:9], vcc
	s_cbranch_execz .LBB0_2446
	s_bcnt1_i32_b64 s4, s[4:5]
	v_mov_b32_e32 v1, 0
	v_mov_b32_e32 v2, s4
.LBB0_2446:
	s_or_b64 exec, exec, s[8:9]
	s_waitcnt vmcnt(0)

.LBB0_2538:
	s_or_b64 exec, exec, s[4:5]
	s_mov_b64 s[4:5], exec
	v_mbcnt_lo_u32_b32 v1, s4, 0
	v_mbcnt_hi_u32_b32 v1, s5, v1
	v_cmp_eq_u32_e32 vcc, 0, v1
	s_and_saveexec_b64 s[8:9], vcc
	s_cbranch_execz .LBB0_2540
	s_bcnt1_i32_b64 s4, s[4:5]
	v_mov_b32_e32 v1, 0
	v_mov_b32_e32 v2, s4
.LBB0_2540:
	s_or_b64 exec, exec, s[8:9]
	s_waitcnt vmcnt(0)

.LBB0_2635:
	s_or_b64 exec, exec, s[4:5]
	s_mov_b64 s[4:5], exec
	v_mbcnt_lo_u32_b32 v1, s4, 0
	v_mbcnt_hi_u32_b32 v1, s5, v1
	v_cmp_eq_u32_e32 vcc, 0, v1
	s_and_saveexec_b64 s[8:9], vcc
	s_cbranch_execz .LBB0_2637
	s_bcnt1_i32_b64 s4, s[4:5]
	v_mov_b32_e32 v1, 0
	v_mov_b32_e32 v2, s4
.LBB0_2637:
	s_or_b64 exec, exec, s[8:9]
	s_waitcnt vmcnt(0)

.LBB0_2715:
	s_or_b64 exec, exec, s[4:5]
	s_mov_b64 s[4:5], exec
	v_mbcnt_lo_u32_b32 v1, s4, 0
	v_mbcnt_hi_u32_b32 v1, s5, v1
	v_cmp_eq_u32_e32 vcc, 0, v1
	s_and_saveexec_b64 s[8:9], vcc
	s_cbranch_execz .LBB0_2717
	s_bcnt1_i32_b64 s4, s[4:5]
	v_mov_b32_e32 v1, 0
	v_mov_b32_e32 v2, s4
.LBB0_2717:
	s_or_b64 exec, exec, s[8:9]
	s_waitcnt vmcnt(0)

.LBB0_2809:
	s_or_b64 exec, exec, s[4:5]
	s_mov_b64 s[4:5], exec
	v_mbcnt_lo_u32_b32 v1, s4, 0
	v_mbcnt_hi_u32_b32 v1, s5, v1
	v_cmp_eq_u32_e32 vcc, 0, v1
	s_and_saveexec_b64 s[8:9], vcc
	s_cbranch_execz .LBB0_2811
	s_bcnt1_i32_b64 s4, s[4:5]
	v_mov_b32_e32 v1, 0
	v_mov_b32_e32 v2, s4
.LBB0_2811:
	s_or_b64 exec, exec, s[8:9]
	s_waitcnt vmcnt(0)

.LBB0_2906:
	s_or_b64 exec, exec, s[4:5]
	s_mov_b64 s[4:5], exec
	v_mbcnt_lo_u32_b32 v1, s4, 0
	v_mbcnt_hi_u32_b32 v1, s5, v1
	v_cmp_eq_u32_e32 vcc, 0, v1
	s_and_saveexec_b64 s[8:9], vcc
	s_cbranch_execz .LBB0_2908
	s_bcnt1_i32_b64 s4, s[4:5]
	v_mov_b32_e32 v1, 0
	v_mov_b32_e32 v2, s4
.LBB0_2908:
	s_or_b64 exec, exec, s[8:9]
	s_waitcnt vmcnt(0)

.LBB0_2978:
	s_or_b64 exec, exec, s[4:5]
	s_mov_b64 s[4:5], exec
	v_mbcnt_lo_u32_b32 v1, s4, 0
	v_mbcnt_hi_u32_b32 v1, s5, v1
	v_cmp_eq_u32_e32 vcc, 0, v1
	s_and_saveexec_b64 s[8:9], vcc
	s_cbranch_execz .LBB0_2980
	s_bcnt1_i32_b64 s4, s[4:5]
	v_mov_b32_e32 v1, 0
	v_mov_b32_e32 v2, s4
.LBB0_2980:
	s_or_b64 exec, exec, s[8:9]
	s_waitcnt vmcnt(0)

.LBB0_3076:
	s_or_b64 exec, exec, s[4:5]
	s_mov_b64 s[4:5], exec
	v_mbcnt_lo_u32_b32 v1, s4, 0
	v_mbcnt_hi_u32_b32 v1, s5, v1
	v_cmp_eq_u32_e32 vcc, 0, v1
	s_and_saveexec_b64 s[8:9], vcc
	s_cbranch_execz .LBB0_3078
	s_bcnt1_i32_b64 s4, s[4:5]
	v_mov_b32_e32 v1, 0
	v_mov_b32_e32 v2, s4
.LBB0_3078:
	s_or_b64 exec, exec, s[8:9]
	s_waitcnt vmcnt(0)

.LBB0_3139:
	s_or_b64 exec, exec, s[4:5]
	s_mov_b64 s[4:5], exec
	v_mbcnt_lo_u32_b32 v1, s4, 0
	v_mbcnt_hi_u32_b32 v1, s5, v1
	v_cmp_eq_u32_e32 vcc, 0, v1
	s_and_saveexec_b64 s[8:9], vcc
	s_cbranch_execz .LBB0_3141
	s_bcnt1_i32_b64 s4, s[4:5]
	v_mov_b32_e32 v1, 0
	v_mov_b32_e32 v2, s4
.LBB0_3141:
	s_or_b64 exec, exec, s[8:9]
	s_waitcnt vmcnt(0)

.LBB0_3200:
	s_or_b64 exec, exec, s[4:5]
	s_mov_b64 s[4:5], exec
	v_mbcnt_lo_u32_b32 v1, s4, 0
	v_mbcnt_hi_u32_b32 v1, s5, v1
	v_cmp_eq_u32_e32 vcc, 0, v1
	s_and_saveexec_b64 s[8:9], vcc
	s_cbranch_execz .LBB0_3202
	s_bcnt1_i32_b64 s4, s[4:5]
	v_mov_b32_e32 v1, 0
	v_mov_b32_e32 v2, s4
.LBB0_3202:
	s_or_b64 exec, exec, s[8:9]
	s_waitcnt vmcnt(0)

.LBB0_3281:
	s_or_b64 exec, exec, s[4:5]
	s_mov_b64 s[4:5], exec
	v_mbcnt_lo_u32_b32 v1, s4, 0
	v_mbcnt_hi_u32_b32 v1, s5, v1
	v_cmp_eq_u32_e32 vcc, 0, v1
	s_and_saveexec_b64 s[8:9], vcc
	s_cbranch_execz .LBB0_3283
	s_bcnt1_i32_b64 s4, s[4:5]
	v_mov_b32_e32 v1, 0
	v_mov_b32_e32 v2, s4
.LBB0_3283:
	s_or_b64 exec, exec, s[8:9]
	s_waitcnt vmcnt(0)

.LBB0_3361:
	s_or_b64 exec, exec, s[4:5]
	s_mov_b64 s[4:5], exec
	v_mbcnt_lo_u32_b32 v1, s4, 0
	v_mbcnt_hi_u32_b32 v1, s5, v1
	v_cmp_eq_u32_e32 vcc, 0, v1
	s_and_saveexec_b64 s[8:9], vcc
	s_cbranch_execz .LBB0_3363
	s_bcnt1_i32_b64 s4, s[4:5]
	v_mov_b32_e32 v1, 0
	v_mov_b32_e32 v2, s4
.LBB0_3363:
	s_or_b64 exec, exec, s[8:9]
	s_waitcnt vmcnt(0)

.LBB0_3455:
	s_or_b64 exec, exec, s[4:5]
	s_mov_b64 s[4:5], exec
	v_mbcnt_lo_u32_b32 v1, s4, 0
	v_mbcnt_hi_u32_b32 v1, s5, v1
	v_cmp_eq_u32_e32 vcc, 0, v1
	s_and_saveexec_b64 s[8:9], vcc
	s_cbranch_execz .LBB0_3457
	s_bcnt1_i32_b64 s3, s[4:5]
	v_mov_b32_e32 v1, 0
	v_mov_b32_e32 v2, s3
.LBB0_3457:
	s_or_b64 exec, exec, s[8:9]
	s_waitcnt vmcnt(0)

.LBB0_3551:
	s_or_b64 exec, exec, s[8:9]
	s_and_saveexec_b64 s[2:3], s[10:11]
	s_cbranch_execz .LBB0_3553
	v_mov_b32_e32 v1, 1
	global_atomic_add v[2:3], v1, off
	v_mov_b32_e32 v5, 0
	global_atomic_add v5, v1, s[100:101] offset:-4096
	global_atomic_add v5, v1, s[100:101] offset:-3840
	global_atomic_add v5, v1, s[100:101] offset:-3584
	global_atomic_add v5, v1, s[100:101] offset:-3328
	global_atomic_add v5, v1, s[100:101] offset:-3072
	global_atomic_add v5, v1, s[100:101] offset:-2816
	global_atomic_add v5, v1, s[100:101] offset:-2560
	global_atomic_add v5, v1, s[100:101] offset:-2304
	global_atomic_add v5, v1, s[100:101] offset:-2048
	global_atomic_add v5, v1, s[100:101] offset:-1792
	global_atomic_add v5, v1, s[100:101] offset:-1536
	global_atomic_add v5, v1, s[100:101] offset:-1280
	global_atomic_add v5, v1, s[100:101] offset:-1024
	global_atomic_add v5, v1, s[100:101] offset:-768
	global_atomic_add v5, v1, s[100:101] offset:-512
	global_atomic_add v5, v1, s[100:101] offset:-256
.LBB0_3553:
	s_or_b64 exec, exec, s[2:3]
	s_mov_b64 s[2:3], exec
	v_mbcnt_lo_u32_b32 v1, s2, 0
	v_mbcnt_hi_u32_b32 v1, s3, v1
	v_cmp_eq_u32_e32 vcc, 0, v1
	s_and_saveexec_b64 s[6:7], vcc
	s_cbranch_execz .LBB0_3555
	s_bcnt1_i32_b64 s2, s[2:3]
	v_mov_b32_e32 v1, 0
	v_mov_b32_e32 v2, s2
.LBB0_3555:
	s_or_b64 exec, exec, s[6:7]
	s_waitcnt vmcnt(0)

.LBB0_3621:
	s_or_b64 exec, exec, s[8:9]
	s_and_saveexec_b64 s[2:3], s[10:11]
	s_cbranch_execz .LBB0_3623
	v_mov_b32_e32 v2, 1
	global_atomic_add v[0:1], v2, off
	v_mov_b32_e32 v5, 0
	global_atomic_add v5, v2, s[100:101] offset:-4096
	global_atomic_add v5, v2, s[100:101] offset:-3840
	global_atomic_add v5, v2, s[100:101] offset:-3584
	global_atomic_add v5, v2, s[100:101] offset:-3328
	global_atomic_add v5, v2, s[100:101] offset:-3072
	global_atomic_add v5, v2, s[100:101] offset:-2816
	global_atomic_add v5, v2, s[100:101] offset:-2560
	global_atomic_add v5, v2, s[100:101] offset:-2304
	global_atomic_add v5, v2, s[100:101] offset:-2048
	global_atomic_add v5, v2, s[100:101] offset:-1792
	global_atomic_add v5, v2, s[100:101] offset:-1536
	global_atomic_add v5, v2, s[100:101] offset:-1280
	global_atomic_add v5, v2, s[100:101] offset:-1024
	global_atomic_add v5, v2, s[100:101] offset:-768
	global_atomic_add v5, v2, s[100:101] offset:-512
	global_atomic_add v5, v2, s[100:101] offset:-256
.LBB0_3623:
	s_or_b64 exec, exec, s[2:3]
	s_mov_b64 s[2:3], exec
	v_mbcnt_lo_u32_b32 v0, s2, 0
	v_mbcnt_hi_u32_b32 v0, s3, v0
	v_cmp_eq_u32_e32 vcc, 0, v0
	s_and_saveexec_b64 s[6:7], vcc
	s_cbranch_execz .LBB0_3625
	s_bcnt1_i32_b64 s2, s[2:3]
	v_mov_b32_e32 v0, 0
	v_mov_b32_e32 v1, s2
.LBB0_3625:
	s_or_b64 exec, exec, s[6:7]
	s_waitcnt vmcnt(0)
